# post_diff cache-conversion loop rotated: next iteration loads issued before the wave-sum chain and stores
# baseline (speedup 1.0000x reference)
.LBB0_966:
	s_movk_i32 s0, 0x3fff
	v_cmp_lt_i32_e32 vcc, s0, v26
	s_and_saveexec_b64 s[0:1], vcc
	s_xor_b64 s[16:17], exec, s[0:1]
	s_cbranch_execz .LBB0_969
	v_add_u32_e32 v7, 0xffffc000, v26
	v_lshrrev_b32_e32 v0, 8, v34
	v_lshrrev_b32_e32 v8, 8, v7
	v_mul_hi_u32_u24_e32 v1, 0x880000, v0
	v_mul_u32_u24_e32 v0, 0x880000, v0
	v_and_b32_e32 v6, 0xff, v70
	v_mul_hi_u32_u24_e32 v7, 0x1100, v8
	v_mul_u32_u24_e32 v8, 0x1100, v8
	v_mov_b32_e32 v35, v112
	v_lshl_or_b32 v0, v6, 1, v0
	v_or_b32_e32 v6, v8, v6
	v_lshlrev_b64 v[4:5], 12, v[34:35]
	v_lshlrev_b64 v[6:7], 11, v[6:7]
	v_lshl_add_u64 v[0:1], v[32:33], 0, v[0:1]
	v_lshl_add_u64 v[2:3], v[38:39], 0, v[4:5]
	v_lshl_add_u64 v[4:5], v[40:41], 0, v[4:5]
	v_lshl_add_u64 v[6:7], v[36:37], 0, v[6:7]
	s_mov_b64 s[18:19], 0
	global_load_dword v12, v[4:5], off
	global_load_dword v13, v[2:3], off
	s_waitcnt vmcnt(0)
.LBB0_968:
	v_cvt_pk_bf16_f32 v8, v12, s0
	v_cvt_pk_bf16_f32 v14, v13, s0
	s_add_u32 s18, s18, 0x100
	s_addc_u32 s19, s19, 0
	s_cmpk_eq_i32 s18, 0x1000
	s_cbranch_scc1 .Lpd_nopf
	v_lshl_add_u64 v[16:17], v[4:5], 0, s[18:19]
	global_load_dword v12, v[16:17], off
	v_lshl_add_u64 v[16:17], v[2:3], 0, s[18:19]
	global_load_dword v13, v[16:17], off
.Lpd_nopf:
	v_mov_b32_e32 v11, v192
	v_lshlrev_b32_e32 v9, 16, v8
	v_lshlrev_b32_e32 v11, 2, v11
	v_mul_f32_e32 v10, v9, v9
	v_bitop3_b32 v11, v11, s33, v203 bitop3:0x6c
	ds_bpermute_b32 v10, v11, v10
	s_waitcnt lgkmcnt(0)
	v_fmac_f32_e32 v10, v9, v9
	v_mov_b32_e32 v9, v192
	s_nop 0
	v_lshlrev_b32_e32 v9, 2, v9
	v_bitop3_b32 v9, v9, 64, v203 bitop3:0x6c
	ds_bpermute_b32 v9, v9, v10
	s_waitcnt lgkmcnt(0)
	v_add_f32_e32 v9, v10, v9
	v_mov_b32_e32 v10, v192
	s_nop 0
	v_lshlrev_b32_e32 v10, 2, v10
	v_bitop3_b32 v10, v10, 32, v203 bitop3:0x6c
	ds_bpermute_b32 v10, v10, v9
	s_waitcnt lgkmcnt(0)
	v_add_f32_e32 v9, v9, v10
	v_mov_b32_e32 v10, v192
	s_nop 0
	v_lshlrev_b32_e32 v10, 2, v10
	v_bitop3_b32 v10, v10, 16, v203 bitop3:0x6c
	ds_bpermute_b32 v10, v10, v9
	s_waitcnt lgkmcnt(0)
	v_add_f32_e32 v9, v9, v10
	v_mov_b32_e32 v10, v192
	s_nop 0
	v_lshlrev_b32_e32 v10, 2, v10
	v_bitop3_b32 v10, v10, 8, v203 bitop3:0x6c
	ds_bpermute_b32 v10, v10, v9
	s_waitcnt lgkmcnt(0)
	v_add_f32_e32 v9, v9, v10
	v_mov_b32_e32 v10, v192
	global_store_short v[6:7], v8, off
	v_lshlrev_b32_e32 v10, 2, v10
	v_bitop3_b32 v10, v10, 4, v203 bitop3:0x6c
	ds_bpermute_b32 v10, v10, v9
	v_lshl_add_u64 v[6:7], v[6:7], 0, s[94:95]
	s_waitcnt lgkmcnt(0)
	v_add_f32_e32 v9, v9, v10
	v_max_f32_e32 v10, v71, v71
	v_max_f32_e32 v71, v10, v9
	s_mov_b64 s[0:1], 0x88000
	global_store_short v[0:1], v14, off
	v_lshl_add_u64 v[0:1], v[0:1], 0, s[0:1]
	s_cmpk_lg_i32 s18, 0x1000
	s_waitcnt vmcnt(2)
	s_cbranch_scc1 .LBB0_968
